# GLA chunk cumsum: the four waves each prefix-sum 16 of the 64 rows and add a 3-term offset, instead of one wave walking all 64 rows
# speedup vs baseline: 1.0072x; 1.0072x over previous
; DI void gla_chain_mfma(const P& p, int cid, char* smem) {
;     ...
;       if (tid < 64) {
;         float run = 0.f;
; #pragma unroll 8
;         for (int j = 0; j < 64; ++j) { run += BC[j * 65 + tid]; BC[j * 65 + tid] = run; }
;       }
.LBB0_727:
	s_waitcnt lgkmcnt(0)
	s_barrier
	v_lshrrev_b32_e32 v253, 6, v132
	v_mov_b32_e32 v254, 0xf40
	v_mad_u32_u24 v252, v253, v254, v156
	ds_read_b32 v224, v252 offset:0
	ds_read_b32 v225, v252 offset:260
	ds_read_b32 v226, v252 offset:520
	ds_read_b32 v227, v252 offset:780
	ds_read_b32 v228, v252 offset:1040
	ds_read_b32 v229, v252 offset:1300
	ds_read_b32 v230, v252 offset:1560
	ds_read_b32 v231, v252 offset:1820
	ds_read_b32 v232, v252 offset:2080
	ds_read_b32 v233, v252 offset:2340
	ds_read_b32 v234, v252 offset:2600
	ds_read_b32 v235, v252 offset:2860
	ds_read_b32 v236, v252 offset:3120
	ds_read_b32 v237, v252 offset:3380
	ds_read_b32 v238, v252 offset:3640
	ds_read_b32 v239, v252 offset:3900
	v_lshlrev_b32_e32 v251, 8, v253
	v_sub_u32_e32 v251, v156, v251
	s_waitcnt lgkmcnt(0)
	v_add_f32_e32 v225, v224, v225
	v_add_f32_e32 v226, v225, v226
	v_add_f32_e32 v227, v226, v227
	v_add_f32_e32 v228, v227, v228
	v_add_f32_e32 v229, v228, v229
	v_add_f32_e32 v230, v229, v230
	v_add_f32_e32 v231, v230, v231
	v_add_f32_e32 v232, v231, v232
	v_add_f32_e32 v233, v232, v233
	v_add_f32_e32 v234, v233, v234
	v_add_f32_e32 v235, v234, v235
	v_add_f32_e32 v236, v235, v236
	v_add_f32_e32 v237, v236, v237
	v_add_f32_e32 v238, v237, v238
	v_add_f32_e32 v239, v238, v239
	ds_write_b32 v156, v239 offset:16640
	s_waitcnt lgkmcnt(0)
	s_barrier
	ds_read_b32 v240, v251 offset:16640
	ds_read_b32 v241, v251 offset:16896
	ds_read_b32 v242, v251 offset:17152
	s_waitcnt lgkmcnt(0)
	v_cmp_lt_u32_e32 vcc, 0, v253
	s_nop 1
	v_cndmask_b32_e32 v240, 0, v240, vcc
	v_cmp_lt_u32_e32 vcc, 1, v253
	s_nop 1
	v_cndmask_b32_e32 v241, 0, v241, vcc
	v_cmp_lt_u32_e32 vcc, 2, v253
	s_nop 1
	v_cndmask_b32_e32 v242, 0, v242, vcc
	v_add_f32_e32 v240, v240, v241
	v_add_f32_e32 v240, v240, v242
	v_add_f32_e32 v224, v240, v224
	v_add_f32_e32 v225, v240, v225
	v_add_f32_e32 v226, v240, v226
	v_add_f32_e32 v227, v240, v227
	v_add_f32_e32 v228, v240, v228
	v_add_f32_e32 v229, v240, v229
	v_add_f32_e32 v230, v240, v230
	v_add_f32_e32 v231, v240, v231
	v_add_f32_e32 v232, v240, v232
	v_add_f32_e32 v233, v240, v233
	v_add_f32_e32 v234, v240, v234
	v_add_f32_e32 v235, v240, v235
	v_add_f32_e32 v236, v240, v236
	v_add_f32_e32 v237, v240, v237
	v_add_f32_e32 v238, v240, v238
	v_add_f32_e32 v239, v240, v239
	ds_write_b32 v252, v224 offset:0
	ds_write_b32 v252, v225 offset:260
	ds_write_b32 v252, v226 offset:520
	ds_write_b32 v252, v227 offset:780
	ds_write_b32 v252, v228 offset:1040
	ds_write_b32 v252, v229 offset:1300
	ds_write_b32 v252, v230 offset:1560
	ds_write_b32 v252, v231 offset:1820
	ds_write_b32 v252, v232 offset:2080
	ds_write_b32 v252, v233 offset:2340
	ds_write_b32 v252, v234 offset:2600
	ds_write_b32 v252, v235 offset:2860
	ds_write_b32 v252, v236 offset:3120
	ds_write_b32 v252, v237 offset:3380
	ds_write_b32 v252, v238 offset:3640
	ds_write_b32 v252, v239 offset:3900
